# seam 3 (out-proj -> gate GEMM): per-panel-group arrival counter (8 WGs sharing a row panel) replaces the domain-wide xcd arrive/wait; assumes panel mates share an XCD L2
# speedup vs baseline: 1.0027x; 1.0005x over previous
; #define PG8_WAIT_V(n) asm volatile("s_waitcnt vmcnt(" #n ")" ::: "memory")
; #define PG8_BAR __builtin_amdgcn_s_barrier()
; __device__ __forceinline__ int lane_id() { int l; asm volatile("v_mbcnt_lo_u32_b32 %0, -1, 0\n\tv_mbcnt_hi_u32_b32 %0, -1, %0" : "=v"(l)); return l; }
; __device__ __forceinline__ unsigned xb_add(unsigned* p, unsigned v) { return __hip_atomic_fetch_add(p, v, __ATOMIC_RELAXED, __HIP_MEMORY_SCOPE_AGENT); }
; template <class Epi, class Sched, bool ALIGN_EPI = false, bool SP2 = false>
; __device__ __forceinline__ void gemm_phase(PG8_LAS unsigned char* lds, const Gemm g, const Sched& S, const Epi& E, const int wave_id) {
;     ...
;     PG8_WAIT_V(0);
;     if constexpr (!ALIGN_EPI) { if (wr == 0) PG8_BAR; }
;     PG8_BAR;
; __device__ __forceinline__ void xcd_arrive(const XcdBarrier& b) {
;     asm volatile("s_waitcnt vmcnt(0)" ::: "memory");
;     __syncthreads();
;     if (b.w0 != 0 && lane_id() == 0) {
;         unsigned* bar = b.bar;
;         __builtin_amdgcn_s_waitcnt(0);
;         unsigned nloc = b.st[0], nx = b.st[1];
;         if (nloc == 0u) { xcd_barrier_complete(bar, b.x, b.G, nloc, nx); b.st[0] = nloc; b.st[1] = nx; }
;         const unsigned old = xb_add(&bar[XB_XSUB(b.x)], 1u);
;         const unsigned gen = old / nloc;
;         if (old + 1u == (gen + 1u) * nloc) {
;             __builtin_amdgcn_fence(__ATOMIC_RELEASE, "agent");
;             asm volatile("s_waitcnt vmcnt(0)" ::: "memory");
;             const unsigned og = xb_add(&bar[XB_TOP], 1u);
;             const unsigned tg = og / nx;
;             if (og + 1u == (tg + 1u) * nx) xb_add(&bar[XB_TOPGEN], 1u);
;         }
;     }
; }
.LBB0_528:
	s_waitcnt vmcnt(0)
	s_barrier
	s_waitcnt vmcnt(0)
	s_and_b64 vcc, exec, s[94:95]
	s_barrier
	s_cbranch_vccnz .LBB0_554
	v_mbcnt_lo_u32_b32 v0, -1, 0
	v_mbcnt_hi_u32_b32 v0, -1, v0
	s_nop 0
	v_cmp_eq_u32_e32 vcc, 0, v0
	s_and_saveexec_b64 s[6:7], vcc
	s_cbranch_execz .LBB0_553
	v_readlane_b32 s0, v254, 19
	v_readlane_b32 s1, v254, 21
	s_add_i32 s0, s0, s1
	s_lshl_b32 s0, s0, 7
	s_add_u32 s0, s0, 0x7800
	v_mov_b32_e32 v0, s0
	v_mov_b32_e32 v1, 1
	global_atomic_add v0, v1, s[52:53]

; __device__ __forceinline__ u32x4 pack8(const f32x4 a, const f32x4 b) { u32x4 w; w.x = cvt_pk_bf16(a[0], a[1]); w.y = cvt_pk_bf16(a[2], a[3]); w.z = cvt_pk_bf16(b[0], b[1]); w.w = cvt_pk_bf16(b[2], b[3]); return w; }
; __device__ __forceinline__ int lane_id() { int l; asm volatile("v_mbcnt_lo_u32_b32 %0, -1, 0\n\tv_mbcnt_hi_u32_b32 %0, -1, %0" : "=v"(l)); return l; }
; __device__ __forceinline__ unsigned xb_ld(unsigned* p)              { return __hip_atomic_load(p, __ATOMIC_RELAXED, __HIP_MEMORY_SCOPE_AGENT); }
; #define XB_SPIN(cond, bar) do { unsigned _sp = 0; while (cond) { __builtin_amdgcn_s_sleep(1); \
;     if ((++_sp & 255u) == 0u) { if (xb_ld(&(bar)[XB_TMO])) break; if (_sp > XB_SPIN_CAP) { atomicAdd(&(bar)[XB_TMO], 1u); break; } } } } while (0)
;     __device__ __forceinline__ void operator()(const f32x4 (&acc)[2][2][4][2], const Unit& u, int wr, int wc, int fr, int fq) const {
;         const int row0 = u.pm * BM + wr * 64 + fr, col0 = u.pn * BM + wc * 32 + 8 * fq;
; #pragma unroll
;         for (int ai = 0; ai < 2; ++ai)
; #pragma unroll
;             for (int m = 0; m < 4; ++m) { bf16_t* rowp = O + (size_t)(row0 + ai * HALF + m * 16) * ldc + col0;
; #pragma unroll
;                 for (int bj = 0; bj < 2; ++bj) *(u32x4*)(rowp + bj * HALF) = pack8(acc[ai][bj][m][0], acc[ai][bj][m][1]); }
;     }
; __device__ __forceinline__ void xcd_wait(const XcdBarrier& b, unsigned use) {
;     if (b.w0 != 0 && lane_id() == 0) {
;         unsigned* bar = b.bar;
;         XB_SPIN(xb_ld(&bar[XB_TOPGEN]) <= use, bar);
;         __builtin_amdgcn_fence(__ATOMIC_ACQUIRE, "agent");
;         asm volatile("s_waitcnt vmcnt(0)" ::: "memory");
;     }
;     __syncthreads();
; }
.LBB0_558:
	v_lshl_add_u32 v130, s6, 8, v128
	v_ashrrev_i32_e32 v131, 31, v130
	v_or_b32_e32 v132, s97, v129
	v_lshlrev_b64 v[128:129], 12, v[130:131]
	v_lshl_add_u64 v[128:129], s[2:3], 0, v[128:129]
	v_lshlrev_b32_e32 v224, 1, v132
	v_mov_b32_e32 v225, 0
	v_lshl_add_u64 v[128:129], v[128:129], 0, v[224:225]
	v_cvt_pk_bf16_f32 v120, v120, v121
	v_cvt_pk_bf16_f32 v121, v122, v123
	v_cvt_pk_bf16_f32 v122, v112, v113
	v_cvt_pk_bf16_f32 v123, v114, v115
	global_store_dwordx4 v[128:129], v[120:123], off
	v_cvt_pk_bf16_f32 v112, v124, v125
	v_cvt_pk_bf16_f32 v113, v126, v127
	v_cvt_pk_bf16_f32 v114, v116, v117
	v_cvt_pk_bf16_f32 v115, v118, v119
	global_store_dwordx4 v[128:129], v[112:115], off offset:256
	v_cvt_pk_bf16_f32 v104, v104, v105
	v_cvt_pk_bf16_f32 v105, v106, v107
	v_cvt_pk_bf16_f32 v106, v96, v97
	v_cvt_pk_bf16_f32 v107, v98, v99
	s_mov_b64 s[0:1], 0x80000
	s_nop 0
	v_or_b32_e32 v112, 16, v130
	v_ashrrev_i32_e32 v113, 31, v112
	v_lshlrev_b64 v[112:113], 12, v[112:113]
	v_lshl_add_u64 v[112:113], s[2:3], 0, v[112:113]
	v_lshl_add_u64 v[112:113], v[112:113], 0, v[224:225]
	global_store_dwordx4 v[112:113], v[104:107], off
	v_cvt_pk_bf16_f32 v96, v108, v109
	v_cvt_pk_bf16_f32 v97, v110, v111
	v_cvt_pk_bf16_f32 v98, v100, v101
	v_cvt_pk_bf16_f32 v99, v102, v103
	global_store_dwordx4 v[112:113], v[96:99], off offset:256
	v_cvt_pk_bf16_f32 v88, v88, v89
	v_cvt_pk_bf16_f32 v89, v90, v91
	v_cvt_pk_bf16_f32 v90, v80, v81
	v_cvt_pk_bf16_f32 v91, v82, v83
	s_mov_b32 s42, 0
	s_nop 0
	v_or_b32_e32 v96, 32, v130
	v_ashrrev_i32_e32 v97, 31, v96
	v_lshlrev_b64 v[96:97], 12, v[96:97]
	v_lshl_add_u64 v[96:97], s[2:3], 0, v[96:97]
	v_lshl_add_u64 v[96:97], v[96:97], 0, v[224:225]
	global_store_dwordx4 v[96:97], v[88:91], off
	v_cvt_pk_bf16_f32 v80, v92, v93
	v_cvt_pk_bf16_f32 v81, v94, v95
	v_cvt_pk_bf16_f32 v82, v84, v85
	v_cvt_pk_bf16_f32 v83, v86, v87
	global_store_dwordx4 v[96:97], v[80:83], off offset:256
	v_cvt_pk_bf16_f32 v56, v56, v57
	v_cvt_pk_bf16_f32 v57, v58, v59
	v_cvt_pk_bf16_f32 v58, v48, v49
	v_cvt_pk_bf16_f32 v59, v50, v51
	s_nop 1
	v_or_b32_e32 v80, 48, v130
	v_ashrrev_i32_e32 v81, 31, v80
	v_lshlrev_b64 v[80:81], 12, v[80:81]
	v_lshl_add_u64 v[80:81], s[2:3], 0, v[80:81]
	v_lshl_add_u64 v[80:81], v[80:81], 0, v[224:225]
	global_store_dwordx4 v[80:81], v[56:59], off
	v_cvt_pk_bf16_f32 v48, v60, v61
	v_cvt_pk_bf16_f32 v49, v62, v63
	v_cvt_pk_bf16_f32 v50, v52, v53
	v_lshl_add_u64 v[52:53], v[128:129], 0, s[0:1]
	s_mov_b32 s0, 0x80000
	v_cvt_pk_bf16_f32 v51, v54, v55
	v_add_co_u32_e32 v54, vcc, s0, v128
	global_store_dwordx4 v[80:81], v[48:51], off offset:256
	s_nop 0
	v_addc_co_u32_e32 v55, vcc, 0, v129, vcc
	v_cvt_pk_bf16_f32 v48, v76, v77
	v_cvt_pk_bf16_f32 v49, v78, v79
	v_cvt_pk_bf16_f32 v50, v72, v73
	v_cvt_pk_bf16_f32 v51, v74, v75
	global_store_dwordx4 v[54:55], v[48:51], off
	s_mov_b64 s[0:1], 0x90000
	s_nop 0
	v_cvt_pk_bf16_f32 v48, v68, v69
	v_cvt_pk_bf16_f32 v49, v70, v71
	v_cvt_pk_bf16_f32 v50, v64, v65
	v_cvt_pk_bf16_f32 v51, v66, v67
	global_store_dwordx4 v[52:53], v[48:51], off offset:256
	v_cvt_pk_bf16_f32 v44, v44, v45
	v_cvt_pk_bf16_f32 v45, v46, v47
	v_cvt_pk_bf16_f32 v46, v36, v37
	v_cvt_pk_bf16_f32 v47, v38, v39
	s_nop 1
	v_lshl_add_u64 v[48:49], v[128:129], 0, s[0:1]
	s_mov_b32 s0, 0x90000
	v_add_co_u32_e32 v36, vcc, s0, v128
	s_mov_b64 s[0:1], 0xa0000
	s_nop 0
	v_addc_co_u32_e32 v37, vcc, 0, v129, vcc
	global_store_dwordx4 v[36:37], v[44:47], off
	v_cvt_pk_bf16_f32 v36, v40, v41
	v_cvt_pk_bf16_f32 v37, v42, v43
	v_cvt_pk_bf16_f32 v38, v32, v33
	v_lshl_add_u64 v[32:33], v[128:129], 0, s[0:1]
	s_mov_b32 s0, 0xa0000
	v_cvt_pk_bf16_f32 v39, v34, v35
	global_store_dwordx4 v[48:49], v[36:39], off offset:256
	v_cvt_pk_bf16_f32 v28, v28, v29
	v_cvt_pk_bf16_f32 v29, v30, v31
	v_cvt_pk_bf16_f32 v30, v20, v21
	v_add_co_u32_e32 v20, vcc, s0, v128
	s_mov_b64 s[0:1], 0xb0000
	s_nop 0
	v_addc_co_u32_e32 v21, vcc, 0, v129, vcc
	v_cvt_pk_bf16_f32 v31, v22, v23
	global_store_dwordx4 v[20:21], v[28:31], off
	v_cvt_pk_bf16_f32 v20, v24, v25
	v_cvt_pk_bf16_f32 v21, v26, v27
	v_cvt_pk_bf16_f32 v22, v16, v17
	v_lshl_add_u64 v[16:17], v[128:129], 0, s[0:1]
	s_mov_b32 s0, 0xb0000
	v_cvt_pk_bf16_f32 v23, v18, v19
	global_store_dwordx4 v[32:33], v[20:23], off offset:256
	v_cvt_pk_bf16_f32 v12, v12, v13
	v_cvt_pk_bf16_f32 v13, v14, v15
	v_cvt_pk_bf16_f32 v14, v4, v5
	v_add_co_u32_e32 v4, vcc, s0, v128
	v_cvt_pk_bf16_f32 v15, v6, v7
	s_nop 1
	v_addc_co_u32_e32 v5, vcc, 0, v129, vcc
	global_store_dwordx4 v[4:5], v[12:15], off
	v_cvt_pk_bf16_f32 v4, v8, v9
	v_cvt_pk_bf16_f32 v5, v10, v11
	v_cvt_pk_bf16_f32 v6, v0, v1
	v_cvt_pk_bf16_f32 v7, v2, v3
	global_store_dwordx4 v[16:17], v[4:7], off offset:256
	s_waitcnt vmcnt(0)
	s_and_b64 vcc, exec, s[94:95]
	s_barrier
	s_cbranch_vccnz .LBB0_575
	v_mbcnt_lo_u32_b32 v0, -1, 0
	v_mbcnt_hi_u32_b32 v0, -1, v0
	s_nop 0
	v_cmp_eq_u32_e32 vcc, 0, v0
	s_and_saveexec_b64 s[0:1], vcc
	s_cbranch_execz .LBB0_574
	v_readlane_b32 s6, v254, 19
	v_readlane_b32 s7, v254, 21
	s_add_i32 s6, s6, s7
	s_lshl_b32 s6, s6, 7
	s_add_u32 s6, s6, 0x7800
	v_mov_b32_e32 v0, s6
	s_movk_i32 s13, 0x4000
.Lpn3_poll:
	global_load_dword v1, v0, s[52:53] sc1
	s_waitcnt vmcnt(0)
	v_cmp_lt_u32_e32 vcc, 7, v1
	s_cbranch_vccnz .Lpn3_got
	s_sleep 1
	s_sub_u32 s13, s13, 1
	s_cmp_lg_u32 s13, 0
	s_cbranch_scc1 .Lpn3_poll
.Lpn3_got:
.LBB0_573:
	s_waitcnt vmcnt(0)
	buffer_inv sc1
	s_waitcnt vmcnt(0)
